# m12 plus: copy-2 gate waves skip staging; rsqrt row factors computed in tile prologue; pure gate tiles skip post-loop barriers
# speedup vs baseline: 1.0043x; 1.0043x over previous
; DI void stage_acc(const f32x4 (&acc)[4][4], float* tile, int wm, int wn, int fr, int fq) {
; #pragma unroll
;   for (int mi = 0; mi < 4; ++mi)
; #pragma unroll
;     for (int ni = 0; ni < 4; ++ni)
; #pragma unroll
;       for (int j = 0; j < 4; ++j) tile[(wm * 64 + mi * 16 + fq * 4 + j) * EPS + wn * 64 + ni * 16 + fr] = acc[mi][ni][j];
; }
; DI void phaseA_tile(const P& p, int layer, int mt, int nt, char* lds) {
;     ...
;   const int wm = wave >> 1, wn = wave & 1;
;   const int seg = (col0 >> 6) + wn;
;   const int fr = lane & 15, fq = lane >> 4;
;   if (tid < 128) {
;     const float ss = (ssa.x + ssa.y + ssa.z + ssa.w) + (ssb.x + ssb.y + ssb.z + ssb.w) + (ssc.x + ssc.y + ssc.z + ssc.w) + (ssd.x + ssd.y + ssd.z + ssd.w);
;     rr[tid] = rsqrtf(ss * (1.f / 1024.f) + 1e-6f);
;   }
;   float* stg = (float*)lds;
;   stage_acc(acc, stg, wm, wn, fr, fq);
;   __syncthreads();
;   if (seg >= NSEG) return;
.LBB0_1597:
	s_or_b64 exec, exec, s[0:1]
	s_ashr_i32 s48, s4, 7
	s_bfe_u32 s0, s4, 0x10006
	v_bfe_u32 v88, v92, 4, 2
	v_and_b32_e32 v89, 15, v92
	s_lshl_b32 s7, s48, 6
	v_lshlrev_b32_e32 v127, 2, v88
	s_lshl_b32 s49, s0, 8
	s_lshl_b32 s16, s37, 1
	v_or_b32_e32 v66, s7, v127
	v_lshl_or_b32 v0, v89, 2, s49
	s_or_b32 s29, s0, s16
	v_mad_u64_u32 v[66:67], s[0:1], v66, s56, v[0:1]
	s_cmp_gt_i32 s29, 52
	s_cbranch_scc1 .Lstg_skip_a2
	v_add_u32_e32 v0, 0x400, v66
	ds_write2_b32 v66, v62, v58 offset1:16
	ds_write2_b32 v66, v63, v59 offset0:132 offset1:148
	ds_write2_b32 v0, v64, v60 offset0:8 offset1:24
	ds_write2_b32 v0, v65, v61 offset0:140 offset1:156
	ds_write2_b32 v66, v54, v50 offset0:32 offset1:48
	ds_write2_b32 v66, v55, v51 offset0:164 offset1:180
	ds_write2_b32 v0, v56, v52 offset0:40 offset1:56
	ds_write2_b32 v0, v57, v53 offset0:172 offset1:188
	v_add_u32_e32 v0, 0x2000, v66
	v_add_u32_e32 v67, 0x2400, v66
	ds_write2_b32 v0, v46, v42 offset0:64 offset1:80
	ds_write2_b32 v0, v47, v43 offset0:196 offset1:212
	ds_write2_b32 v67, v48, v44 offset0:72 offset1:88
	ds_write2_b32 v67, v49, v45 offset0:204 offset1:220
	ds_write2_b32 v0, v38, v34 offset0:96 offset1:112
	ds_write2_b32 v0, v39, v35 offset0:228 offset1:244
	ds_write2_b32 v67, v40, v36 offset0:104 offset1:120
	ds_write2_b32 v67, v41, v37 offset0:236 offset1:252
	v_add_u32_e32 v0, 0x4000, v66
	v_add_u32_e32 v67, 0x4400, v66
	v_add_u32_e32 v68, 0x4800, v66
	ds_write2_b32 v0, v30, v26 offset0:128 offset1:144
	ds_write2_b32 v67, v31, v27 offset0:4 offset1:20
	ds_write2_b32 v67, v32, v28 offset0:136 offset1:152
	ds_write2_b32 v68, v33, v29 offset0:12 offset1:28
	ds_write2_b32 v0, v22, v18 offset0:160 offset1:176
	ds_write2_b32 v67, v23, v19 offset0:36 offset1:52
	ds_write2_b32 v67, v24, v20 offset0:168 offset1:184
	ds_write2_b32 v68, v25, v21 offset0:44 offset1:60
	v_add_u32_e32 v0, 0x6000, v66
	v_add_u32_e32 v67, 0x6400, v66
	v_add_u32_e32 v66, 0x6800, v66
	ds_write2_b32 v0, v14, v10 offset0:192 offset1:208
	ds_write2_b32 v67, v15, v11 offset0:68 offset1:84
	ds_write2_b32 v67, v16, v12 offset0:200 offset1:216
	ds_write2_b32 v66, v17, v13 offset0:76 offset1:92
	ds_write2_b32 v0, v6, v2 offset0:224 offset1:240
	ds_write2_b32 v67, v7, v3 offset0:100 offset1:116
	ds_write2_b32 v67, v8, v4 offset0:232 offset1:248
	ds_write2_b32 v66, v9, v5 offset0:108 offset1:124
.Lstg_skip_a2:
	s_cmpk_gt_i32 s29, 0x54
	s_movk_i32 s5, 0x2000
	s_waitcnt lgkmcnt(0)
	s_barrier
	s_cbranch_scc1 .LBB0_1588
	v_and_b32_e32 v152, 63, v92
	s_cmp_lt_i32 s29, 53
	s_mov_b64 s[0:1], -1
	s_cbranch_scc0 .LBB0_1985
	s_cmpk_gt_i32 s36, 0xff
	s_cselect_b64 s[38:39], -1, 0
	s_cmpk_lt_i32 s36, 0x100
	s_cselect_b64 s[8:9], -1, 0
	s_and_b32 s0, s37, 0x7ffffffc
	s_cmp_lg_u32 s0, 16
	s_cbranch_scc1 .LBB0_1665
	v_lshlrev_b32_e32 v0, 2, v127
	v_lshl_add_u32 v0, s7, 2, v0
	s_add_i32 s12, s7, s6
	v_add_u32_e32 v80, 0x10800, v0
	s_ashr_i32 s0, s12, 8
	ds_read_b128 v[66:69], v80
	s_sub_i32 s10, s29, 32
	s_and_b32 s0, s0, -8
	s_or_b32 s0, s0, s10
	s_ashr_i32 s1, s0, 31
	s_lshl_b64 s[0:1], s[0:1], 18
	s_mov_b64 s[4:5], -1
	s_and_b64 vcc, exec, s[8:9]
	v_lshlrev_b32_e32 v70, 12, v89
	s_cbranch_vccz .LBB0_1602
	v_readlane_b32 s4, v240, 52
	s_add_u32 s4, s4, s0
	v_readlane_b32 s5, v240, 53
	s_addc_u32 s5, s5, s1
	v_mov_b32_e32 v71, v1
	v_lshl_add_u64 v[72:73], s[4:5], 0, v[70:71]
	s_mov_b64 s[4:5], 0
